# filler w_in transpose items: 31 gain loads issued together (one wait); EpiFinal: 4 row partials in one dwordx4 load; barS sweep pipelined
# baseline (speedup 1.0000x reference)
.LBB0_708:
	s_waitcnt vmcnt(0) lgkmcnt(0)
	s_barrier
	s_lshl_b32 s33, s40, 8
	s_and_saveexec_b64 s[2:3], s[0:1]
	s_cbranch_execz .LBB0_710
	s_waitcnt lgkmcnt(0)
	v_add_u32_e32 v132, s33, v18
	v_readlane_b32 s0, v248, 59
	v_ashrrev_i32_e32 v133, 31, v132
	v_readlane_b32 s1, v248, 60
	v_lshl_add_u32 v18, v18, 2, 0
	v_add_u32_e32 v18, 0x21200, v18
	v_lshl_add_u64 v[132:133], v[132:133], 4, s[0:1]
	global_load_dwordx4 v[132:135], v[132:133], off sc1
	s_waitcnt vmcnt(0)
	v_add_f32_e32 v19, 0, v132
	v_add_f32_e32 v19, v19, v133
	v_add_f32_e32 v19, v19, v134
	v_add_f32_e32 v19, v19, v135
	v_fmamk_f32 v19, v19, 0x3a800000, v218
	v_rsq_f32_e32 v19, v19
	ds_write_b32 v18, v19

.LBB0_900:
	s_andn2_b64 vcc, exec, s[6:7]
	s_mov_b32 s6, 0
	s_cbranch_vccnz .LBB0_926
	v_readlane_b32 s16, v252, 1
	v_readlane_b32 s22, v252, 7
	v_readlane_b32 s23, v252, 8
	s_add_u32 s8, s22, s0
	s_addc_u32 s9, s23, s1
	s_lshl_b32 s0, s2, 10
	s_ashr_i32 s1, s0, 31
	v_readlane_b32 s20, v252, 5
	s_lshl_b64 s[0:1], s[0:1], 2
	v_readlane_b32 s21, v252, 6
	s_add_u32 s6, s20, s0
	s_addc_u32 s7, s21, s1
	s_add_i32 s0, s10, 0xf880
	s_lshr_b32 s0, s0, 1
	s_and_b32 s13, s0, 0x7fc0
	s_lshl_b32 s0, s10, 5
	s_and_b32 s11, s0, 0xfe0
	s_lshl_b32 s0, s11, 2
	s_add_u32 s0, s8, s0
	v_or_b32_e32 v57, s13, v0
	s_addc_u32 s1, s9, 0
	v_lshlrev_b32_e32 v6, 2, v2
	v_mov_b32_e32 v7, v16
	v_lshl_add_u64 v[6:7], s[0:1], 0, v[6:7]
	v_lshlrev_b32_e32 v8, 14, v57
	v_mov_b32_e32 v9, v16
	v_lshl_add_u64 v[6:7], v[6:7], 0, v[8:9]
	s_mov_b32 s0, 0x8000
	v_add_co_u32_e32 v8, vcc, s0, v6
	s_mov_b32 s0, 0x10000
	s_nop 0
	v_addc_co_u32_e32 v9, vcc, 0, v7, vcc
	global_load_dword v53, v[6:7], off
	global_load_dword v54, v[8:9], off
	v_add_co_u32_e32 v8, vcc, s0, v6
	s_mov_b32 s0, 0x18000
	s_nop 0
	v_addc_co_u32_e32 v9, vcc, 0, v7, vcc
	global_load_dword v55, v[8:9], off
	v_add_co_u32_e32 v8, vcc, s0, v6
	s_mov_b32 s0, 0x20000
	s_nop 0
	v_addc_co_u32_e32 v9, vcc, 0, v7, vcc
	global_load_dword v56, v[8:9], off
	v_add_co_u32_e32 v8, vcc, s0, v6
	s_mov_b32 s0, 0x28000
	s_nop 0
	v_addc_co_u32_e32 v9, vcc, 0, v7, vcc
	global_load_dword v49, v[8:9], off
	v_add_co_u32_e32 v8, vcc, s0, v6
	s_mov_b32 s0, 0x30000
	s_nop 0
	v_addc_co_u32_e32 v9, vcc, 0, v7, vcc
	global_load_dword v50, v[8:9], off
	v_add_co_u32_e32 v8, vcc, s0, v6
	s_mov_b32 s0, 0x38000
	s_nop 0
	v_addc_co_u32_e32 v9, vcc, 0, v7, vcc
	global_load_dword v51, v[8:9], off
	v_add_co_u32_e32 v8, vcc, s0, v6
	s_mov_b32 s0, 0x40000
	s_nop 0
	v_addc_co_u32_e32 v9, vcc, 0, v7, vcc
	global_load_dword v52, v[8:9], off
	v_add_co_u32_e32 v8, vcc, s0, v6
	s_mov_b32 s0, 0x48000
	s_nop 0
	v_addc_co_u32_e32 v9, vcc, 0, v7, vcc
	global_load_dword v45, v[8:9], off
	v_add_co_u32_e32 v8, vcc, s0, v6
	s_mov_b32 s0, 0x50000
	s_nop 0
	v_addc_co_u32_e32 v9, vcc, 0, v7, vcc
	global_load_dword v46, v[8:9], off
	v_add_co_u32_e32 v8, vcc, s0, v6
	s_mov_b32 s0, 0x58000
	s_nop 0
	v_addc_co_u32_e32 v9, vcc, 0, v7, vcc
	global_load_dword v47, v[8:9], off
	v_add_co_u32_e32 v8, vcc, s0, v6
	s_mov_b32 s0, 0x60000
	s_nop 0
	v_addc_co_u32_e32 v9, vcc, 0, v7, vcc
	global_load_dword v48, v[8:9], off
	v_add_co_u32_e32 v8, vcc, s0, v6
	s_mov_b32 s0, 0x68000
	s_nop 0
	v_addc_co_u32_e32 v9, vcc, 0, v7, vcc
	global_load_dword v41, v[8:9], off
	v_add_co_u32_e32 v8, vcc, s0, v6
	s_mov_b32 s0, 0x70000
	s_nop 0
	v_addc_co_u32_e32 v9, vcc, 0, v7, vcc
	global_load_dword v42, v[8:9], off
	v_add_co_u32_e32 v8, vcc, s0, v6
	s_mov_b32 s0, 0x78000
	s_nop 0
	v_addc_co_u32_e32 v9, vcc, 0, v7, vcc
	global_load_dword v43, v[8:9], off
	v_add_co_u32_e32 v8, vcc, s0, v6
	s_mov_b32 s0, 0x80000
	s_nop 0
	v_addc_co_u32_e32 v9, vcc, 0, v7, vcc
	global_load_dword v44, v[8:9], off
	v_add_co_u32_e32 v8, vcc, s0, v6
	s_mov_b32 s0, 0x88000
	s_nop 0
	v_addc_co_u32_e32 v9, vcc, 0, v7, vcc
	global_load_dword v37, v[8:9], off
	v_add_co_u32_e32 v8, vcc, s0, v6
	s_mov_b32 s0, 0x90000
	s_nop 0
	v_addc_co_u32_e32 v9, vcc, 0, v7, vcc
	global_load_dword v38, v[8:9], off
	v_add_co_u32_e32 v8, vcc, s0, v6
	s_mov_b32 s0, 0x98000
	s_nop 0
	v_addc_co_u32_e32 v9, vcc, 0, v7, vcc
	global_load_dword v39, v[8:9], off
	v_add_co_u32_e32 v8, vcc, s0, v6
	s_mov_b32 s0, 0xa0000
	s_nop 0
	v_addc_co_u32_e32 v9, vcc, 0, v7, vcc
	global_load_dword v40, v[8:9], off
	v_add_co_u32_e32 v8, vcc, s0, v6
	s_mov_b32 s0, 0xa8000
	s_nop 0
	v_addc_co_u32_e32 v9, vcc, 0, v7, vcc
	global_load_dword v32, v[8:9], off
	v_add_co_u32_e32 v8, vcc, s0, v6
	s_mov_b32 s0, 0xb0000
	s_nop 0
	v_addc_co_u32_e32 v9, vcc, 0, v7, vcc
	global_load_dword v34, v[8:9], off
	v_add_co_u32_e32 v8, vcc, s0, v6
	s_mov_b32 s0, 0xb8000
	s_nop 0
	v_addc_co_u32_e32 v9, vcc, 0, v7, vcc
	global_load_dword v35, v[8:9], off
	v_add_co_u32_e32 v8, vcc, s0, v6
	s_mov_b32 s0, 0xc0000
	s_nop 0
	v_addc_co_u32_e32 v9, vcc, 0, v7, vcc
	global_load_dword v36, v[8:9], off
	v_add_co_u32_e32 v8, vcc, s0, v6
	s_mov_b32 s0, 0xc8000
	s_nop 0
	v_addc_co_u32_e32 v9, vcc, 0, v7, vcc
	global_load_dword v29, v[8:9], off
	v_add_co_u32_e32 v8, vcc, s0, v6
	s_mov_b32 s0, 0xd0000
	s_nop 0
	v_addc_co_u32_e32 v9, vcc, 0, v7, vcc
	global_load_dword v30, v[8:9], off
	v_add_co_u32_e32 v8, vcc, s0, v6
	s_mov_b32 s0, 0xd8000
	s_nop 0
	v_addc_co_u32_e32 v9, vcc, 0, v7, vcc
	global_load_dword v31, v[8:9], off
	v_add_co_u32_e32 v8, vcc, s0, v6
	s_mov_b32 s0, 0xe0000
	s_nop 0
	v_addc_co_u32_e32 v9, vcc, 0, v7, vcc
	global_load_dword v33, v[8:9], off
	v_add_co_u32_e32 v8, vcc, s0, v6
	v_readlane_b32 s8, v248, 44
	s_nop 0
	v_addc_co_u32_e32 v9, vcc, 0, v7, vcc
	v_add_co_u32_e32 v58, vcc, 0xe8000, v6
	global_load_dword v8, v[8:9], off
	s_nop 0
	v_addc_co_u32_e32 v59, vcc, 0, v7, vcc
	global_load_dword v9, v[58:59], off
	v_add_co_u32_e32 v58, vcc, 0xf0000, v6
	v_readlane_b32 s9, v248, 45
	s_nop 0
	v_addc_co_u32_e32 v59, vcc, 0, v7, vcc
	v_add_co_u32_e32 v6, vcc, 0xf8000, v6
	global_load_dword v28, v[58:59], off
	s_nop 0
	v_addc_co_u32_e32 v7, vcc, 0, v7, vcc
	global_load_dword v6, v[6:7], off
	v_cndmask_b32_e64 v7, 0, 1, s[8:9]
	v_cmp_ne_u32_e64 s[0:1], 1, v7
	s_andn2_b64 vcc, exec, s[8:9]
	v_add_lshl_u32 v7, s13, v0, 2
	v_readlane_b32 s17, v252, 2
	v_readlane_b32 s18, v252, 3
	v_readlane_b32 s19, v252, 4
	v_readlane_b32 s24, v252, 9
	v_readlane_b32 s25, v252, 10
	v_readlane_b32 s26, v252, 11
	v_readlane_b32 s27, v252, 12
	v_readlane_b32 s28, v252, 13
	v_readlane_b32 s29, v252, 14
	v_readlane_b32 s30, v252, 15
	v_readlane_b32 s31, v252, 16
	s_cbranch_vccnz .LBB0_968
	v_lshlrev_b32_e32 v57, 2, v57
	global_load_dword v101, v7, s[6:7] offset:8
	global_load_dword v102, v7, s[6:7] offset:16
	global_load_dword v103, v7, s[6:7] offset:24
	global_load_dword v104, v7, s[6:7] offset:32
	global_load_dword v105, v7, s[6:7] offset:40
	global_load_dword v106, v7, s[6:7] offset:48
	global_load_dword v107, v7, s[6:7] offset:56
	global_load_dword v108, v7, s[6:7] offset:64
	global_load_dword v109, v7, s[6:7] offset:72
	global_load_dword v110, v7, s[6:7] offset:80
	global_load_dword v111, v7, s[6:7] offset:88
	global_load_dword v112, v7, s[6:7] offset:96
	global_load_dword v113, v7, s[6:7] offset:104
	global_load_dword v114, v7, s[6:7] offset:112
	global_load_dword v115, v7, s[6:7] offset:120
	global_load_dword v116, v7, s[6:7] offset:128
	global_load_dword v117, v7, s[6:7] offset:136
	global_load_dword v118, v7, s[6:7] offset:144
	global_load_dword v119, v7, s[6:7] offset:152
	global_load_dword v120, v7, s[6:7] offset:160
	global_load_dword v121, v7, s[6:7] offset:168
	global_load_dword v122, v7, s[6:7] offset:176
	global_load_dword v123, v7, s[6:7] offset:184
	global_load_dword v124, v7, s[6:7] offset:192
	global_load_dword v125, v7, s[6:7] offset:200
	global_load_dword v126, v7, s[6:7] offset:208
	global_load_dword v127, v7, s[6:7] offset:216
	global_load_dword v128, v7, s[6:7] offset:224
	global_load_dword v129, v7, s[6:7] offset:232
	global_load_dword v130, v7, s[6:7] offset:240
	global_load_dword v131, v7, s[6:7] offset:248
	global_load_dword v57, v57, s[6:7]
	v_add_u32_e32 v59, v5, v10
	s_waitcnt vmcnt(0)
	v_mov_b32_e32 v58, v101
	v_mul_f32_e32 v57, v53, v57
	ds_write_b32 v59, v57
	s_waitcnt vmcnt(0)
	v_mul_f32_e32 v57, v54, v58
	v_add_u32_e32 v58, v5, v17
	ds_write_b32 v58, v57
	v_mov_b32_e32 v57, v102
	v_mov_b32_e32 v58, v103
	s_waitcnt vmcnt(1)
	v_mul_f32_e32 v57, v55, v57
	s_cbranch_execnz .LBB0_904

.LBB0_904:
	s_waitcnt vmcnt(31)
	v_add_u32_e32 v53, v5, v18
	s_waitcnt vmcnt(0)
	v_mul_f32_e32 v54, v56, v58
	s_and_b64 vcc, exec, s[0:1]
	ds_write2_b32 v53, v57, v54 offset1:66
	s_cbranch_vccnz .LBB0_969
	v_mov_b32_e32 v53, v104
	v_mov_b32_e32 v54, v105
	v_add_u32_e32 v55, v5, v19
	s_waitcnt vmcnt(1)
	v_mul_f32_e32 v53, v49, v53
	s_waitcnt vmcnt(0)
	v_mul_f32_e32 v54, v50, v54
	ds_write2_b32 v55, v53, v54 offset1:66
	v_mov_b32_e32 v53, v106
	v_mov_b32_e32 v54, v107
	s_waitcnt vmcnt(1)
	v_mul_f32_e32 v53, v51, v53
	s_cbranch_execnz .LBB0_907

.LBB0_907:
	v_add_u32_e32 v49, v5, v20
	s_waitcnt vmcnt(0)
	v_mul_f32_e32 v50, v52, v54
	s_and_b64 vcc, exec, s[0:1]
	ds_write2_b32 v49, v53, v50 offset1:66
	s_cbranch_vccnz .LBB0_970
	v_mov_b32_e32 v49, v108
	v_mov_b32_e32 v50, v109
	v_add_u32_e32 v51, v5, v21
	s_waitcnt vmcnt(1)
	v_mul_f32_e32 v49, v45, v49
	s_waitcnt vmcnt(0)
	v_mul_f32_e32 v50, v46, v50
	ds_write2_b32 v51, v49, v50 offset1:66
	v_mov_b32_e32 v49, v110
	v_mov_b32_e32 v50, v111
	s_waitcnt vmcnt(1)
	v_mul_f32_e32 v49, v47, v49
	s_cbranch_execnz .LBB0_910

.LBB0_910:
	v_add_u32_e32 v45, v5, v22
	s_waitcnt vmcnt(0)
	v_mul_f32_e32 v46, v48, v50
	s_and_b64 vcc, exec, s[0:1]
	ds_write2_b32 v45, v49, v46 offset1:66
	s_cbranch_vccnz .LBB0_971
	v_mov_b32_e32 v45, v112
	v_mov_b32_e32 v46, v113
	v_add_u32_e32 v47, v5, v23
	s_waitcnt vmcnt(1)
	v_mul_f32_e32 v45, v41, v45
	s_waitcnt vmcnt(0)
	v_mul_f32_e32 v46, v42, v46
	ds_write2_b32 v47, v45, v46 offset1:66
	v_mov_b32_e32 v45, v114
	v_mov_b32_e32 v46, v115
	s_waitcnt vmcnt(1)
	v_mul_f32_e32 v45, v43, v45
	s_cbranch_execnz .LBB0_913

.LBB0_913:
	v_add_u32_e32 v41, v5, v24
	s_waitcnt vmcnt(0)
	v_mul_f32_e32 v42, v44, v46
	s_and_b64 vcc, exec, s[0:1]
	ds_write2_b32 v41, v45, v42 offset1:66
	s_cbranch_vccnz .LBB0_972
	v_mov_b32_e32 v41, v116
	v_mov_b32_e32 v42, v117
	v_add_u32_e32 v43, v5, v25
	s_waitcnt vmcnt(1)
	v_mul_f32_e32 v41, v37, v41
	s_waitcnt vmcnt(0)
	v_mul_f32_e32 v42, v38, v42
	ds_write2_b32 v43, v41, v42 offset1:66
	v_mov_b32_e32 v41, v118
	v_mov_b32_e32 v42, v119
	s_waitcnt vmcnt(1)
	v_mul_f32_e32 v41, v39, v41
	s_cbranch_execnz .LBB0_916

.LBB0_916:
	v_add_u32_e32 v37, v5, v26
	s_waitcnt vmcnt(0)
	v_mul_f32_e32 v38, v40, v42
	s_and_b64 vcc, exec, s[0:1]
	ds_write2_b32 v37, v41, v38 offset1:66
	s_cbranch_vccnz .LBB0_973
	v_mov_b32_e32 v37, v120
	v_mov_b32_e32 v38, v121
	v_add_u32_e32 v39, v5, v27
	s_waitcnt vmcnt(1)
	v_mul_f32_e32 v37, v32, v37
	s_waitcnt vmcnt(0)
	v_mul_f32_e32 v38, v34, v38
	ds_write2_b32 v39, v37, v38 offset1:66
	v_mov_b32_e32 v37, v122
	v_mov_b32_e32 v38, v123
	s_waitcnt vmcnt(1)
	v_mul_f32_e32 v37, v35, v37
	s_cbranch_execnz .LBB0_919

.LBB0_919:
	v_add_u32_e32 v32, v5, v27
	s_waitcnt vmcnt(0)
	v_mul_f32_e32 v34, v36, v38
	ds_write2_b32 v32, v37, v34 offset0:132 offset1:198
	s_and_b64 vcc, exec, s[0:1]
	v_add_u32_e32 v34, 0x400, v32
	s_cbranch_vccnz .LBB0_974
	v_mov_b32_e32 v35, v124
	v_mov_b32_e32 v36, v125
	s_waitcnt vmcnt(1)
	v_mul_f32_e32 v35, v29, v35
	s_waitcnt vmcnt(0)
	v_mul_f32_e32 v36, v30, v36
	ds_write2_b32 v34, v35, v36 offset0:8 offset1:74
	v_mov_b32_e32 v35, v126
	v_mov_b32_e32 v36, v127
	s_waitcnt vmcnt(1)
	v_mul_f32_e32 v35, v31, v35
	s_cbranch_execnz .LBB0_922

.LBB0_922:
	s_waitcnt vmcnt(0)
	v_mul_f32_e32 v29, v33, v36
	ds_write2_b32 v34, v35, v29 offset0:140 offset1:206
	s_and_b64 vcc, exec, s[0:1]
	v_add_u32_e32 v29, 0x800, v32
	s_cbranch_vccnz .LBB0_975
	v_mov_b32_e32 v30, v128
	v_mov_b32_e32 v31, v129
	s_waitcnt vmcnt(1)
	v_mul_f32_e32 v30, v8, v30
	s_waitcnt vmcnt(0)
	v_mul_f32_e32 v31, v9, v31
	ds_write2_b32 v29, v30, v31 offset0:16 offset1:82
	v_mov_b32_e32 v30, v130
	s_waitcnt vmcnt(0)
	v_mul_f32_e32 v30, v28, v30
	v_mov_b32_e32 v7, v131
	s_cbranch_execnz .LBB0_925

.LBB0_1387:
	s_andn2_b64 vcc, exec, s[6:7]
	s_mov_b32 s6, 0
	s_cbranch_vccnz .LBB0_1413
	v_readlane_b32 s16, v252, 1
	v_readlane_b32 s22, v252, 7
	v_readlane_b32 s23, v252, 8
	s_add_u32 s8, s22, s0
	s_addc_u32 s9, s23, s1
	s_lshl_b32 s0, s2, 10
	s_ashr_i32 s1, s0, 31
	v_readlane_b32 s20, v252, 5
	s_lshl_b64 s[0:1], s[0:1], 2
	v_readlane_b32 s21, v252, 6
	s_add_u32 s6, s20, s0
	s_addc_u32 s7, s21, s1
	s_add_i32 s0, s10, 0xf880
	s_lshr_b32 s0, s0, 1
	s_and_b32 s15, s0, 0x7fc0
	s_lshl_b32 s0, s10, 5
	s_and_b32 s11, s0, 0xfe0
	s_lshl_b32 s0, s11, 2
	s_add_u32 s0, s8, s0
	v_or_b32_e32 v57, s15, v0
	s_addc_u32 s1, s9, 0
	v_lshlrev_b32_e32 v6, 2, v2
	v_mov_b32_e32 v7, v16
	v_lshl_add_u64 v[6:7], s[0:1], 0, v[6:7]
	v_lshlrev_b32_e32 v8, 14, v57
	v_mov_b32_e32 v9, v16
	v_lshl_add_u64 v[6:7], v[6:7], 0, v[8:9]
	s_mov_b32 s0, 0x8000
	v_add_co_u32_e32 v8, vcc, s0, v6
	s_mov_b32 s0, 0x10000
	s_nop 0
	v_addc_co_u32_e32 v9, vcc, 0, v7, vcc
	global_load_dword v53, v[6:7], off
	global_load_dword v54, v[8:9], off
	v_add_co_u32_e32 v8, vcc, s0, v6
	s_mov_b32 s0, 0x18000
	s_nop 0
	v_addc_co_u32_e32 v9, vcc, 0, v7, vcc
	global_load_dword v55, v[8:9], off
	v_add_co_u32_e32 v8, vcc, s0, v6
	s_mov_b32 s0, 0x20000
	s_nop 0
	v_addc_co_u32_e32 v9, vcc, 0, v7, vcc
	global_load_dword v56, v[8:9], off
	v_add_co_u32_e32 v8, vcc, s0, v6
	s_mov_b32 s0, 0x28000
	s_nop 0
	v_addc_co_u32_e32 v9, vcc, 0, v7, vcc
	global_load_dword v49, v[8:9], off
	v_add_co_u32_e32 v8, vcc, s0, v6
	s_mov_b32 s0, 0x30000
	s_nop 0
	v_addc_co_u32_e32 v9, vcc, 0, v7, vcc
	global_load_dword v50, v[8:9], off
	v_add_co_u32_e32 v8, vcc, s0, v6
	s_mov_b32 s0, 0x38000
	s_nop 0
	v_addc_co_u32_e32 v9, vcc, 0, v7, vcc
	global_load_dword v51, v[8:9], off
	v_add_co_u32_e32 v8, vcc, s0, v6
	s_mov_b32 s0, 0x40000
	s_nop 0
	v_addc_co_u32_e32 v9, vcc, 0, v7, vcc
	global_load_dword v52, v[8:9], off
	v_add_co_u32_e32 v8, vcc, s0, v6
	s_mov_b32 s0, 0x48000
	s_nop 0
	v_addc_co_u32_e32 v9, vcc, 0, v7, vcc
	global_load_dword v45, v[8:9], off
	v_add_co_u32_e32 v8, vcc, s0, v6
	s_mov_b32 s0, 0x50000
	s_nop 0
	v_addc_co_u32_e32 v9, vcc, 0, v7, vcc
	global_load_dword v46, v[8:9], off
	v_add_co_u32_e32 v8, vcc, s0, v6
	s_mov_b32 s0, 0x58000
	s_nop 0
	v_addc_co_u32_e32 v9, vcc, 0, v7, vcc
	global_load_dword v47, v[8:9], off
	v_add_co_u32_e32 v8, vcc, s0, v6
	s_mov_b32 s0, 0x60000
	s_nop 0
	v_addc_co_u32_e32 v9, vcc, 0, v7, vcc
	global_load_dword v48, v[8:9], off
	v_add_co_u32_e32 v8, vcc, s0, v6
	s_mov_b32 s0, 0x68000
	s_nop 0
	v_addc_co_u32_e32 v9, vcc, 0, v7, vcc
	global_load_dword v41, v[8:9], off
	v_add_co_u32_e32 v8, vcc, s0, v6
	s_mov_b32 s0, 0x70000
	s_nop 0
	v_addc_co_u32_e32 v9, vcc, 0, v7, vcc
	global_load_dword v42, v[8:9], off
	v_add_co_u32_e32 v8, vcc, s0, v6
	s_mov_b32 s0, 0x78000
	s_nop 0
	v_addc_co_u32_e32 v9, vcc, 0, v7, vcc
	global_load_dword v43, v[8:9], off
	v_add_co_u32_e32 v8, vcc, s0, v6
	s_mov_b32 s0, 0x80000
	s_nop 0
	v_addc_co_u32_e32 v9, vcc, 0, v7, vcc
	global_load_dword v44, v[8:9], off
	v_add_co_u32_e32 v8, vcc, s0, v6
	s_mov_b32 s0, 0x88000
	s_nop 0
	v_addc_co_u32_e32 v9, vcc, 0, v7, vcc
	global_load_dword v37, v[8:9], off
	v_add_co_u32_e32 v8, vcc, s0, v6
	s_mov_b32 s0, 0x90000
	s_nop 0
	v_addc_co_u32_e32 v9, vcc, 0, v7, vcc
	global_load_dword v38, v[8:9], off
	v_add_co_u32_e32 v8, vcc, s0, v6
	s_mov_b32 s0, 0x98000
	s_nop 0
	v_addc_co_u32_e32 v9, vcc, 0, v7, vcc
	global_load_dword v39, v[8:9], off
	v_add_co_u32_e32 v8, vcc, s0, v6
	s_mov_b32 s0, 0xa0000
	s_nop 0
	v_addc_co_u32_e32 v9, vcc, 0, v7, vcc
	global_load_dword v40, v[8:9], off
	v_add_co_u32_e32 v8, vcc, s0, v6
	s_mov_b32 s0, 0xa8000
	s_nop 0
	v_addc_co_u32_e32 v9, vcc, 0, v7, vcc
	global_load_dword v32, v[8:9], off
	v_add_co_u32_e32 v8, vcc, s0, v6
	s_mov_b32 s0, 0xb0000
	s_nop 0
	v_addc_co_u32_e32 v9, vcc, 0, v7, vcc
	global_load_dword v34, v[8:9], off
	v_add_co_u32_e32 v8, vcc, s0, v6
	s_mov_b32 s0, 0xb8000
	s_nop 0
	v_addc_co_u32_e32 v9, vcc, 0, v7, vcc
	global_load_dword v35, v[8:9], off
	v_add_co_u32_e32 v8, vcc, s0, v6
	s_mov_b32 s0, 0xc0000
	s_nop 0
	v_addc_co_u32_e32 v9, vcc, 0, v7, vcc
	global_load_dword v36, v[8:9], off
	v_add_co_u32_e32 v8, vcc, s0, v6
	s_mov_b32 s0, 0xc8000
	s_nop 0
	v_addc_co_u32_e32 v9, vcc, 0, v7, vcc
	global_load_dword v29, v[8:9], off
	v_add_co_u32_e32 v8, vcc, s0, v6
	s_mov_b32 s0, 0xd0000
	s_nop 0
	v_addc_co_u32_e32 v9, vcc, 0, v7, vcc
	global_load_dword v30, v[8:9], off
	v_add_co_u32_e32 v8, vcc, s0, v6
	s_mov_b32 s0, 0xd8000
	s_nop 0
	v_addc_co_u32_e32 v9, vcc, 0, v7, vcc
	global_load_dword v31, v[8:9], off
	v_add_co_u32_e32 v8, vcc, s0, v6
	s_mov_b32 s0, 0xe0000
	s_nop 0
	v_addc_co_u32_e32 v9, vcc, 0, v7, vcc
	global_load_dword v33, v[8:9], off
	v_add_co_u32_e32 v8, vcc, s0, v6
	v_readlane_b32 s8, v248, 44
	s_nop 0
	v_addc_co_u32_e32 v9, vcc, 0, v7, vcc
	v_add_co_u32_e32 v58, vcc, 0xe8000, v6
	global_load_dword v8, v[8:9], off
	s_nop 0
	v_addc_co_u32_e32 v59, vcc, 0, v7, vcc
	global_load_dword v9, v[58:59], off
	v_add_co_u32_e32 v58, vcc, 0xf0000, v6
	v_readlane_b32 s9, v248, 45
	s_nop 0
	v_addc_co_u32_e32 v59, vcc, 0, v7, vcc
	v_add_co_u32_e32 v6, vcc, 0xf8000, v6
	global_load_dword v28, v[58:59], off
	s_nop 0
	v_addc_co_u32_e32 v7, vcc, 0, v7, vcc
	global_load_dword v6, v[6:7], off
	v_cndmask_b32_e64 v7, 0, 1, s[8:9]
	v_cmp_ne_u32_e64 s[0:1], 1, v7
	s_andn2_b64 vcc, exec, s[8:9]
	v_add_lshl_u32 v7, s15, v0, 2
	v_readlane_b32 s17, v252, 2
	v_readlane_b32 s18, v252, 3
	v_readlane_b32 s19, v252, 4
	v_readlane_b32 s24, v252, 9
	v_readlane_b32 s25, v252, 10
	v_readlane_b32 s26, v252, 11
	v_readlane_b32 s27, v252, 12
	v_readlane_b32 s28, v252, 13
	v_readlane_b32 s29, v252, 14
	v_readlane_b32 s30, v252, 15
	v_readlane_b32 s31, v252, 16
	s_cbranch_vccnz .LBB0_1455
	v_lshlrev_b32_e32 v57, 2, v57
	global_load_dword v101, v7, s[6:7] offset:8
	global_load_dword v102, v7, s[6:7] offset:16
	global_load_dword v103, v7, s[6:7] offset:24
	global_load_dword v104, v7, s[6:7] offset:32
	global_load_dword v105, v7, s[6:7] offset:40
	global_load_dword v106, v7, s[6:7] offset:48
	global_load_dword v107, v7, s[6:7] offset:56
	global_load_dword v108, v7, s[6:7] offset:64
	global_load_dword v109, v7, s[6:7] offset:72
	global_load_dword v110, v7, s[6:7] offset:80
	global_load_dword v111, v7, s[6:7] offset:88
	global_load_dword v112, v7, s[6:7] offset:96
	global_load_dword v113, v7, s[6:7] offset:104
	global_load_dword v114, v7, s[6:7] offset:112
	global_load_dword v115, v7, s[6:7] offset:120
	global_load_dword v116, v7, s[6:7] offset:128
	global_load_dword v117, v7, s[6:7] offset:136
	global_load_dword v118, v7, s[6:7] offset:144
	global_load_dword v119, v7, s[6:7] offset:152
	global_load_dword v120, v7, s[6:7] offset:160
	global_load_dword v121, v7, s[6:7] offset:168
	global_load_dword v122, v7, s[6:7] offset:176
	global_load_dword v123, v7, s[6:7] offset:184
	global_load_dword v124, v7, s[6:7] offset:192
	global_load_dword v125, v7, s[6:7] offset:200
	global_load_dword v126, v7, s[6:7] offset:208
	global_load_dword v127, v7, s[6:7] offset:216
	global_load_dword v128, v7, s[6:7] offset:224
	global_load_dword v129, v7, s[6:7] offset:232
	global_load_dword v130, v7, s[6:7] offset:240
	global_load_dword v131, v7, s[6:7] offset:248
	global_load_dword v57, v57, s[6:7]
	v_add_u32_e32 v59, v5, v10
	s_waitcnt vmcnt(0)
	v_mov_b32_e32 v58, v101
	v_mul_f32_e32 v57, v53, v57
	ds_write_b32 v59, v57
	s_waitcnt vmcnt(0)
	v_mul_f32_e32 v57, v54, v58
	v_add_u32_e32 v58, v5, v17
	ds_write_b32 v58, v57
	v_mov_b32_e32 v57, v102
	v_mov_b32_e32 v58, v103
	s_waitcnt vmcnt(1)
	v_mul_f32_e32 v57, v55, v57
	s_cbranch_execnz .LBB0_1391
